# adds: wave priority raised (s_setprio 1/0) around the attention QK and PV MFMA groups, same bracket as the GEMM K-loops
# baseline (speedup 1.0000x reference)
.LBB0_120:
	s_bitcmp1_b32 s86, 0
	s_cselect_b32 s87, 0x4800, 0
	v_add3_u32 v2, s87, v183, v198
	ds_read_b128 v[98:101], v2 offset:4608
	ds_read_b128 v[102:105], v2
	ds_read_b128 v[106:109], v2 offset:32
	ds_read_b128 v[110:113], v2 offset:4672
	v_mov_b64_e32 v[80:81], v[64:65]
	v_mov_b64_e32 v[78:79], v[62:63]
	v_mov_b64_e32 v[76:77], v[60:61]
	v_mov_b64_e32 v[74:75], v[58:59]
	v_mov_b64_e32 v[72:73], v[56:57]
	v_mov_b64_e32 v[70:71], v[54:55]
	v_mov_b64_e32 v[68:69], v[52:53]
	v_mov_b64_e32 v[66:67], v[50:51]
	s_waitcnt lgkmcnt(2)
	s_setprio 1
	v_mfma_f32_32x32x16_bf16 v[82:97], v[102:105], v[130:133], v[50:65]
	ds_read_b128 v[114:117], v2 offset:4640
	s_cmp_lt_u32 s86, 4
	s_cselect_b64 s[2:3], -1, 0
	s_or_b64 s[2:3], s[76:77], s[2:3]
	s_and_b64 vcc, exec, s[2:3]
	v_mfma_f32_32x32x16_bf16 v[66:81], v[98:101], v[130:133], v[66:81]
	ds_read_b128 v[118:121], v2 offset:64
	s_waitcnt lgkmcnt(3)
	v_mfma_f32_32x32x16_bf16 v[82:97], v[106:109], v[134:137], v[82:97]
	ds_read_b128 v[122:125], v2 offset:96
	s_waitcnt lgkmcnt(2)
	v_mfma_f32_32x32x16_bf16 v[66:81], v[114:117], v[134:137], v[66:81]
	ds_read_b128 v[126:129], v2 offset:4704
	s_waitcnt lgkmcnt(2)
	v_mfma_f32_32x32x16_bf16 v[82:97], v[118:121], v[138:141], v[82:97]
	v_mfma_f32_32x32x16_bf16 v[66:81], v[110:113], v[138:141], v[66:81]
	s_waitcnt lgkmcnt(1)
	v_mfma_f32_32x32x16_bf16 v[82:97], v[122:125], v[142:145], v[82:97]
	s_waitcnt lgkmcnt(0)
	v_mfma_f32_32x32x16_bf16 v[66:81], v[126:129], v[142:145], v[66:81]
	s_setprio 0
	s_cbranch_vccnz .LBB0_190
	s_mov_b64 s[2:3], -1
	s_and_b64 vcc, exec, s[70:71]
	s_cbranch_vccz .LBB0_187
	s_add_i32 s2, s85, s86
	v_cmp_ge_i32_e32 vcc, s2, v178
	v_cmp_lt_i32_e64 s[2:3], s2, v180
	v_readlane_b32 s88, v254, 33
	s_and_b64 s[2:3], vcc, s[2:3]
	v_readlane_b32 s89, v254, 34
	s_and_b64 s[88:89], s[2:3], s[88:89]
	v_mov_b32_e32 v114, 0xf149f2ca
	v_mov_b32_e32 v98, 0xf149f2ca
	s_and_saveexec_b64 vcc, s[88:89]
	s_cbranch_execz .LBB0_124
	v_add_u32_e32 v2, v187, v186
	ds_read_b32 v2, v2 offset:37296
	s_waitcnt lgkmcnt(0)
	v_add_f32_e32 v98, v82, v2

.LBB0_195:
	v_lshl_add_u32 v2, v179, 1, s87
	v_add3_u32 v2, v2, v237, v184
	ds_read_b64_tr_b16 v[98:99], v2 offset:9216
	ds_read_b64_tr_b16 v[100:101], v2 offset:10368
	ds_read_b64_tr_b16 v[102:103], v2 offset:9280
	ds_read_b64_tr_b16 v[104:105], v2 offset:10432
	ds_read_b64_tr_b16 v[106:107], v2 offset:11520
	ds_read_b64_tr_b16 v[108:109], v2 offset:12672
	ds_read_b64_tr_b16 v[110:111], v2 offset:11584
	ds_read_b64_tr_b16 v[112:113], v2 offset:12736
	ds_read_b64_tr_b16 v[114:115], v2 offset:13824
	ds_read_b64_tr_b16 v[116:117], v2 offset:14976
	ds_read_b64_tr_b16 v[118:119], v2 offset:13888
	ds_read_b64_tr_b16 v[120:121], v2 offset:15040
	ds_read_b64_tr_b16 v[122:123], v2 offset:16128
	ds_read_b64_tr_b16 v[124:125], v2 offset:17280
	ds_read_b64_tr_b16 v[126:127], v2 offset:16192
	ds_read_b64_tr_b16 v[128:129], v2 offset:17344
	v_exp_f32_e32 v2, v82
	v_exp_f32_e32 v4, v66
	v_exp_f32_e32 v7, v83
	v_exp_f32_e32 v14, v67
	v_exp_f32_e32 v15, v68
	v_add_f32_e32 v6, v4, v2
	v_add_f32_e32 v6, 0, v6
	v_add_f32_e32 v8, v14, v7
	v_add_f32_e32 v6, v8, v6
	v_exp_f32_e32 v8, v84
	v_exp_f32_e32 v16, v69
	v_exp_f32_e32 v17, v70
	v_exp_f32_e32 v66, v71
	v_add_f32_e32 v9, v15, v8
	v_add_f32_e32 v6, v9, v6
	v_exp_f32_e32 v9, v85
	v_exp_f32_e32 v67, v72
	v_exp_f32_e32 v68, v73
	v_exp_f32_e32 v70, v74
	v_add_f32_e32 v10, v16, v9
	v_add_f32_e32 v6, v10, v6
	v_exp_f32_e32 v10, v86
	v_exp_f32_e32 v72, v75
	v_exp_f32_e32 v74, v76
	v_exp_f32_e32 v76, v77
	v_add_f32_e32 v11, v17, v10
	v_add_f32_e32 v6, v11, v6
	v_exp_f32_e32 v11, v87
	v_exp_f32_e32 v78, v78
	v_exp_f32_e32 v79, v79
	v_exp_f32_e32 v80, v80
	v_add_f32_e32 v12, v66, v11
	v_add_f32_e32 v6, v12, v6
	v_exp_f32_e32 v12, v88
	v_exp_f32_e32 v81, v81
	v_subrev_u32_e32 v185, 64, v185
	v_add_u32_e32 v187, 0x7c, v187
	v_add_f32_e32 v13, v67, v12
	v_add_f32_e32 v6, v13, v6
	v_exp_f32_e32 v13, v89
	s_cmp_lg_u32 s84, s2
	v_add_f32_e32 v69, v68, v13
	v_add_f32_e32 v6, v69, v6
	v_exp_f32_e32 v69, v90
	s_nop 0
	v_add_f32_e32 v71, v70, v69
	v_add_f32_e32 v6, v71, v6
	v_exp_f32_e32 v71, v91
	s_nop 0
	v_add_f32_e32 v73, v72, v71
	v_add_f32_e32 v6, v73, v6
	v_exp_f32_e32 v73, v92
	s_nop 0
	v_add_f32_e32 v75, v74, v73
	v_add_f32_e32 v6, v75, v6
	v_exp_f32_e32 v75, v93
	s_nop 0
	v_add_f32_e32 v77, v76, v75
	v_add_f32_e32 v6, v77, v6
	v_exp_f32_e32 v77, v94
	s_nop 0
	v_add_f32_e32 v82, v78, v77
	v_add_f32_e32 v6, v82, v6
	v_exp_f32_e32 v82, v95
	s_nop 0
	v_add_f32_e32 v83, v79, v82
	v_add_f32_e32 v6, v83, v6
	v_exp_f32_e32 v83, v96
	s_nop 0
	v_add_f32_e32 v84, v80, v83
	v_add_f32_e32 v6, v84, v6
	v_exp_f32_e32 v84, v97
	s_nop 0
	v_add_f32_e32 v85, v81, v84
	v_add_f32_e32 v6, v85, v6
	v_lshl_add_u32 v85, v179, 1, s87
	v_add_f32_e32 v5, v5, v6
	v_cvt_pk_bf16_f32 v6, v2, v7
	v_add3_u32 v2, v85, v237, v184
	v_cvt_pk_bf16_f32 v7, v8, v9
	v_cvt_pk_bf16_f32 v8, v10, v11
	v_cvt_pk_bf16_f32 v9, v12, v13
	s_waitcnt lgkmcnt(0)
	s_setprio 1
	v_mfma_f32_32x32x16_bf16 v[18:33], v[98:101], v[6:9], v[18:33]
	s_waitcnt lgkmcnt(0)
	v_mfma_f32_32x32x16_bf16 v[34:49], v[102:105], v[6:9], v[34:49]
	v_cvt_pk_bf16_f32 v6, v69, v71
	v_cvt_pk_bf16_f32 v7, v73, v75
	v_cvt_pk_bf16_f32 v8, v77, v82
	v_cvt_pk_bf16_f32 v9, v83, v84
	s_waitcnt lgkmcnt(0)
	s_nop 0
	v_mfma_f32_32x32x16_bf16 v[18:33], v[106:109], v[6:9], v[18:33]
	s_waitcnt lgkmcnt(0)
	v_mfma_f32_32x32x16_bf16 v[34:49], v[110:113], v[6:9], v[34:49]
	v_cvt_pk_bf16_f32 v6, v4, v14
	v_cvt_pk_bf16_f32 v7, v15, v16
	v_cvt_pk_bf16_f32 v8, v17, v66
	v_cvt_pk_bf16_f32 v9, v67, v68
	s_waitcnt lgkmcnt(0)
	s_nop 0
	v_mfma_f32_32x32x16_bf16 v[18:33], v[114:117], v[6:9], v[18:33]
	s_waitcnt lgkmcnt(0)
	v_mfma_f32_32x32x16_bf16 v[34:49], v[118:121], v[6:9], v[34:49]
	v_cvt_pk_bf16_f32 v6, v70, v72
	v_cvt_pk_bf16_f32 v7, v74, v76
	v_cvt_pk_bf16_f32 v8, v78, v79
	v_cvt_pk_bf16_f32 v9, v80, v81
	s_waitcnt lgkmcnt(0)
	s_nop 0
	v_mfma_f32_32x32x16_bf16 v[18:33], v[122:125], v[6:9], v[18:33]
	s_waitcnt lgkmcnt(0)
	s_barrier
	v_mfma_f32_32x32x16_bf16 v[34:49], v[126:129], v[6:9], v[34:49]
	s_setprio 0
	s_cbranch_scc0 .LBB0_197
	s_mov_b32 s86, s2
	s_branch .LBB0_120

.LBB0_214:
	s_bitcmp1_b32 s77, 0
	s_cselect_b32 s2, 0x5800, 0
	v_add3_u32 v2, s2, v217, v193
	ds_read_b128 v[98:101], v2 offset:6656
	ds_read_b128 v[102:105], v2
	ds_read_b128 v[106:109], v2 offset:32
	ds_read_b128 v[110:113], v2 offset:6720
	v_mov_b64_e32 v[80:81], v[64:65]
	v_mov_b64_e32 v[78:79], v[62:63]
	v_mov_b64_e32 v[76:77], v[60:61]
	v_mov_b64_e32 v[74:75], v[58:59]
	v_mov_b64_e32 v[72:73], v[56:57]
	v_mov_b64_e32 v[70:71], v[54:55]
	v_mov_b64_e32 v[68:69], v[52:53]
	v_mov_b64_e32 v[66:67], v[50:51]
	s_waitcnt lgkmcnt(2)
	s_setprio 1
	v_mfma_f32_32x32x16_bf16 v[82:97], v[102:105], v[130:133], v[50:65]
	ds_read_b128 v[114:117], v2 offset:6688
	s_cmp_lt_u32 s77, 4
	s_cselect_b64 s[38:39], -1, 0
	s_xor_b64 vcc, s[68:69], -1
	s_or_b64 s[38:39], vcc, s[38:39]
	s_and_b64 vcc, exec, s[38:39]
	v_mfma_f32_32x32x16_bf16 v[66:81], v[98:101], v[130:133], v[66:81]
	ds_read_b128 v[118:121], v2 offset:64
	s_waitcnt lgkmcnt(3)
	v_mfma_f32_32x32x16_bf16 v[82:97], v[106:109], v[134:137], v[82:97]
	ds_read_b128 v[122:125], v2 offset:96
	s_waitcnt lgkmcnt(2)
	v_mfma_f32_32x32x16_bf16 v[66:81], v[114:117], v[134:137], v[66:81]
	ds_read_b128 v[126:129], v2 offset:6752
	s_waitcnt lgkmcnt(2)
	v_mfma_f32_32x32x16_bf16 v[82:97], v[118:121], v[138:141], v[82:97]
	ds_read_b128 v[6:9], v2 offset:128
	v_mfma_f32_32x32x16_bf16 v[66:81], v[110:113], v[138:141], v[66:81]
	ds_read_b128 v[10:13], v2 offset:6784
	s_waitcnt lgkmcnt(3)
	v_mfma_f32_32x32x16_bf16 v[82:97], v[122:125], v[142:145], v[82:97]
	ds_read_b128 v[14:17], v2 offset:160
	s_waitcnt lgkmcnt(3)
	v_mfma_f32_32x32x16_bf16 v[66:81], v[126:129], v[142:145], v[66:81]
	ds_read_b128 v[102:105], v2 offset:6816
	s_waitcnt lgkmcnt(3)
	v_mfma_f32_32x32x16_bf16 v[82:97], v[6:9], v[146:149], v[82:97]
	s_waitcnt lgkmcnt(2)
	v_mfma_f32_32x32x16_bf16 v[66:81], v[10:13], v[146:149], v[66:81]
	s_waitcnt lgkmcnt(1)
	v_mfma_f32_32x32x16_bf16 v[82:97], v[14:17], v[150:153], v[82:97]
	s_waitcnt lgkmcnt(0)
	v_mfma_f32_32x32x16_bf16 v[66:81], v[102:105], v[150:153], v[66:81]
	s_setprio 0
	s_cbranch_vccnz .LBB0_284
	s_mov_b64 s[38:39], -1
	s_and_b64 vcc, exec, s[70:71]
	s_cbranch_vccz .LBB0_281
	s_add_i32 s3, s42, s77
	v_cmp_ge_i32_e64 s[38:39], s3, v213
	v_cmp_lt_i32_e32 vcc, s3, v215
	v_readlane_b32 s72, v254, 33
	s_and_b64 s[38:39], s[38:39], vcc
	v_readlane_b32 s73, v254, 34
	s_and_b64 s[72:73], s[38:39], s[72:73]
	v_mov_b32_e32 v114, 0xf149f2ca
	v_mov_b32_e32 v98, 0xf149f2ca
	s_and_saveexec_b64 vcc, s[72:73]
	s_cbranch_execz .LBB0_218
	v_add_u32_e32 v2, v221, v220
	ds_read_b32 v2, v2 offset:45488
	s_waitcnt lgkmcnt(0)
	v_add_f32_e32 v98, v82, v2

.LBB0_289:
	v_lshl_add_u32 v2, v214, 1, s2
	v_add3_u32 v2, v2, v198, v218
	ds_read_b64_tr_b16 v[98:99], v2 offset:13312
	ds_read_b64_tr_b16 v[100:101], v2 offset:14464
	ds_read_b64_tr_b16 v[102:103], v2 offset:13376
	ds_read_b64_tr_b16 v[104:105], v2 offset:14528
	ds_read_b64_tr_b16 v[106:107], v2 offset:15616
	ds_read_b64_tr_b16 v[108:109], v2 offset:16768
	ds_read_b64_tr_b16 v[110:111], v2 offset:15680
	ds_read_b64_tr_b16 v[112:113], v2 offset:16832
	ds_read_b64_tr_b16 v[114:115], v2 offset:17920
	ds_read_b64_tr_b16 v[116:117], v2 offset:19072
	ds_read_b64_tr_b16 v[118:119], v2 offset:17984
	ds_read_b64_tr_b16 v[120:121], v2 offset:19136
	ds_read_b64_tr_b16 v[122:123], v2 offset:20224
	ds_read_b64_tr_b16 v[124:125], v2 offset:21376
	ds_read_b64_tr_b16 v[126:127], v2 offset:20288
	ds_read_b64_tr_b16 v[128:129], v2 offset:21440
	v_exp_f32_e32 v2, v82
	v_exp_f32_e32 v4, v66
	v_exp_f32_e32 v7, v83
	v_exp_f32_e32 v14, v67
	v_exp_f32_e32 v15, v68
	v_add_f32_e32 v6, v4, v2
	v_add_f32_e32 v6, 0, v6
	v_add_f32_e32 v8, v14, v7
	v_add_f32_e32 v6, v8, v6
	v_exp_f32_e32 v8, v84
	v_exp_f32_e32 v16, v69
	v_exp_f32_e32 v17, v70
	v_exp_f32_e32 v66, v71
	v_add_f32_e32 v9, v15, v8
	v_add_f32_e32 v6, v9, v6
	v_exp_f32_e32 v9, v85
	v_exp_f32_e32 v67, v72
	v_exp_f32_e32 v68, v73
	v_exp_f32_e32 v70, v74
	v_add_f32_e32 v10, v16, v9
	v_add_f32_e32 v6, v10, v6
	v_exp_f32_e32 v10, v86
	v_exp_f32_e32 v72, v75
	v_exp_f32_e32 v74, v76
	v_exp_f32_e32 v76, v77
	v_add_f32_e32 v11, v17, v10
	v_add_f32_e32 v6, v11, v6
	v_exp_f32_e32 v11, v87
	v_exp_f32_e32 v78, v78
	v_exp_f32_e32 v79, v79
	v_exp_f32_e32 v80, v80
	v_add_f32_e32 v12, v66, v11
	v_add_f32_e32 v6, v12, v6
	v_exp_f32_e32 v12, v88
	v_exp_f32_e32 v81, v81
	v_subrev_u32_e32 v219, 64, v219
	v_add_u32_e32 v221, 0x7c, v221
	v_add_f32_e32 v13, v67, v12
	v_add_f32_e32 v6, v13, v6
	v_exp_f32_e32 v13, v89
	s_cmp_lg_u32 s76, s3
	v_add_f32_e32 v69, v68, v13
	v_add_f32_e32 v6, v69, v6
	v_exp_f32_e32 v69, v90
	s_nop 0
	v_add_f32_e32 v71, v70, v69
	v_add_f32_e32 v6, v71, v6
	v_exp_f32_e32 v71, v91
	s_nop 0
	v_add_f32_e32 v73, v72, v71
	v_add_f32_e32 v6, v73, v6
	v_exp_f32_e32 v73, v92
	s_nop 0
	v_add_f32_e32 v75, v74, v73
	v_add_f32_e32 v6, v75, v6
	v_exp_f32_e32 v75, v93
	s_nop 0
	v_add_f32_e32 v77, v76, v75
	v_add_f32_e32 v6, v77, v6
	v_exp_f32_e32 v77, v94
	s_nop 0
	v_add_f32_e32 v82, v78, v77
	v_add_f32_e32 v6, v82, v6
	v_exp_f32_e32 v82, v95
	s_nop 0
	v_add_f32_e32 v83, v79, v82
	v_add_f32_e32 v6, v83, v6
	v_exp_f32_e32 v83, v96
	s_nop 0
	v_add_f32_e32 v84, v80, v83
	v_add_f32_e32 v6, v84, v6
	v_exp_f32_e32 v84, v97
	s_nop 0
	v_add_f32_e32 v85, v81, v84
	v_add_f32_e32 v6, v85, v6
	v_lshl_add_u32 v85, v214, 1, s2
	v_add_f32_e32 v5, v5, v6
	v_cvt_pk_bf16_f32 v6, v2, v7
	v_add3_u32 v2, v85, v198, v218
	v_cvt_pk_bf16_f32 v7, v8, v9
	v_cvt_pk_bf16_f32 v8, v10, v11
	v_cvt_pk_bf16_f32 v9, v12, v13
	s_waitcnt lgkmcnt(0)
	s_setprio 1
	v_mfma_f32_32x32x16_bf16 v[18:33], v[98:101], v[6:9], v[18:33]
	s_waitcnt lgkmcnt(0)
	v_mfma_f32_32x32x16_bf16 v[34:49], v[102:105], v[6:9], v[34:49]
	v_cvt_pk_bf16_f32 v6, v69, v71
	v_cvt_pk_bf16_f32 v7, v73, v75
	v_cvt_pk_bf16_f32 v8, v77, v82
	v_cvt_pk_bf16_f32 v9, v83, v84
	s_waitcnt lgkmcnt(0)
	s_nop 0
	v_mfma_f32_32x32x16_bf16 v[18:33], v[106:109], v[6:9], v[18:33]
	s_waitcnt lgkmcnt(0)
	v_mfma_f32_32x32x16_bf16 v[34:49], v[110:113], v[6:9], v[34:49]
	v_cvt_pk_bf16_f32 v6, v4, v14
	v_cvt_pk_bf16_f32 v7, v15, v16
	v_cvt_pk_bf16_f32 v8, v17, v66
	v_cvt_pk_bf16_f32 v9, v67, v68
	s_waitcnt lgkmcnt(0)
	s_nop 0
	v_mfma_f32_32x32x16_bf16 v[18:33], v[114:117], v[6:9], v[18:33]
	s_waitcnt lgkmcnt(0)
	v_mfma_f32_32x32x16_bf16 v[34:49], v[118:121], v[6:9], v[34:49]
	v_cvt_pk_bf16_f32 v6, v70, v72
	v_cvt_pk_bf16_f32 v7, v74, v76
	v_cvt_pk_bf16_f32 v8, v78, v79
	v_cvt_pk_bf16_f32 v9, v80, v81
	s_waitcnt lgkmcnt(0)
	s_nop 0
	v_mfma_f32_32x32x16_bf16 v[18:33], v[122:125], v[6:9], v[18:33]
	s_waitcnt lgkmcnt(0)
	s_barrier
	v_mfma_f32_32x32x16_bf16 v[34:49], v[126:129], v[6:9], v[34:49]
	s_setprio 0
	s_cbranch_scc0 .LBB0_71
	s_mov_b32 s77, s3
	s_branch .LBB0_214
